# v9 + FF1 epilogue: removed redundant canonicalizing v_max before relu (re-padded wide-store WAR)
# speedup vs baseline: 1.0014x; 1.0014x over previous
.LBB0_710:
	v_lshl_add_u32 v164, s28, 8, v151
	v_max_f32_e32 v126, 0, v126
	v_max_f32_e32 v122, 0, v122
	v_max_f32_e32 v127, 0, v127
	v_max_f32_e32 v123, 0, v123
	v_lshl_or_b32 v166, s68, 8, v153
	v_ashrrev_i32_e32 v165, 31, v164
	v_pk_mul_f32 v[126:127], v[126:127], v[126:127]
	v_pk_mul_f32 v[122:123], v[122:123], v[122:123]
	v_max_f32_e32 v128, 0, v128
	v_max_f32_e32 v124, 0, v124
	v_max_f32_e32 v129, 0, v129
	v_max_f32_e32 v125, 0, v125
	v_ashrrev_i32_e32 v167, 31, v166
	v_pk_mul_f32 v[128:129], v[128:129], v[128:129]
	v_pk_mul_f32 v[168:169], v[124:125], v[124:125]
	v_cvt_pk_bf16_f32 v124, v126, v127
	v_cvt_pk_bf16_f32 v126, v122, v123
	v_lshlrev_b64 v[122:123], 14, v[164:165]
	v_cvt_pk_bf16_f32 v125, v128, v129
	v_lshl_add_u64 v[122:123], s[0:1], 0, v[122:123]
	v_lshlrev_b64 v[128:129], 1, v[166:167]
	v_cvt_pk_bf16_f32 v127, v168, v169
	v_lshl_add_u64 v[122:123], v[122:123], 0, v[128:129]
	v_max_f32_e32 v114, 0, v114
	v_max_f32_e32 v115, 0, v115
	global_store_dwordx4 v[122:123], v[124:127], off
	s_nop 1
	v_pk_mul_f32 v[124:125], v[114:115], v[114:115]
	v_max_f32_e32 v115, v116, v116
	v_max_f32_e32 v114, v120, v120
	v_max_f32_e32 v116, 0, v115
	v_max_f32_e32 v115, v121, v121
	v_max_f32_e32 v118, 0, v118
	v_max_f32_e32 v119, 0, v119
	v_max_f32_e32 v114, 0, v114
	v_max_f32_e32 v115, 0, v115
	v_max_f32_e32 v117, 0, v117
	v_pk_mul_f32 v[118:119], v[118:119], v[118:119]
	v_pk_mul_f32 v[120:121], v[114:115], v[114:115]
	v_pk_mul_f32 v[126:127], v[116:117], v[116:117]
	v_cvt_pk_bf16_f32 v114, v118, v119
	v_cvt_pk_bf16_f32 v115, v120, v121
	v_cvt_pk_bf16_f32 v116, v124, v125
	v_cvt_pk_bf16_f32 v117, v126, v127
	v_max_f32_e32 v106, 0, v106
	v_max_f32_e32 v107, 0, v107
	global_store_dwordx4 v[122:123], v[114:117], off offset:256
	s_nop 1
	v_pk_mul_f32 v[116:117], v[106:107], v[106:107]
	v_max_f32_e32 v107, v108, v108
	v_or_b32_e32 v114, 16, v164
	v_max_f32_e32 v110, 0, v110
	v_max_f32_e32 v111, 0, v111
	v_max_f32_e32 v106, v112, v112
	v_max_f32_e32 v108, 0, v107
	v_max_f32_e32 v107, v113, v113
	v_ashrrev_i32_e32 v115, 31, v114
	v_pk_mul_f32 v[110:111], v[110:111], v[110:111]
	v_max_f32_e32 v106, 0, v106
	v_max_f32_e32 v107, 0, v107
	v_max_f32_e32 v109, 0, v109
	v_pk_mul_f32 v[112:113], v[106:107], v[106:107]
	v_cvt_pk_bf16_f32 v106, v110, v111
	v_lshlrev_b64 v[110:111], 14, v[114:115]
	v_pk_mul_f32 v[118:119], v[108:109], v[108:109]
	v_lshl_add_u64 v[110:111], s[0:1], 0, v[110:111]
	v_cvt_pk_bf16_f32 v107, v112, v113
	v_cvt_pk_bf16_f32 v108, v116, v117
	v_cvt_pk_bf16_f32 v109, v118, v119
	v_lshl_add_u64 v[110:111], v[110:111], 0, v[128:129]
	v_max_f32_e32 v98, 0, v98
	v_max_f32_e32 v99, 0, v99
	global_store_dwordx4 v[110:111], v[106:109], off
	s_nop 1
	v_pk_mul_f32 v[106:107], v[98:99], v[98:99]
	v_max_f32_e32 v99, v100, v100
	v_max_f32_e32 v98, v104, v104
	v_max_f32_e32 v100, 0, v99
	v_max_f32_e32 v99, v105, v105
	v_max_f32_e32 v102, 0, v102
	v_max_f32_e32 v103, 0, v103
	v_max_f32_e32 v98, 0, v98
	v_max_f32_e32 v99, 0, v99
	v_max_f32_e32 v101, 0, v101
	v_pk_mul_f32 v[102:103], v[102:103], v[102:103]
	v_pk_mul_f32 v[104:105], v[98:99], v[98:99]
	v_pk_mul_f32 v[108:109], v[100:101], v[100:101]
	v_cvt_pk_bf16_f32 v98, v102, v103
	v_cvt_pk_bf16_f32 v99, v104, v105
	v_cvt_pk_bf16_f32 v100, v106, v107
	v_cvt_pk_bf16_f32 v101, v108, v109
	v_max_f32_e32 v90, 0, v90
	v_max_f32_e32 v91, 0, v91
	global_store_dwordx4 v[110:111], v[98:101], off offset:256
	s_nop 1
	v_pk_mul_f32 v[100:101], v[90:91], v[90:91]
	v_max_f32_e32 v91, v92, v92
	v_or_b32_e32 v98, 32, v164
	v_max_f32_e32 v94, 0, v94
	v_max_f32_e32 v95, 0, v95
	v_max_f32_e32 v90, v96, v96
	v_max_f32_e32 v92, 0, v91
	v_max_f32_e32 v91, v97, v97
	v_ashrrev_i32_e32 v99, 31, v98
	v_pk_mul_f32 v[94:95], v[94:95], v[94:95]
	v_max_f32_e32 v90, 0, v90
	v_max_f32_e32 v91, 0, v91
	v_max_f32_e32 v93, 0, v93
	v_pk_mul_f32 v[96:97], v[90:91], v[90:91]
	v_cvt_pk_bf16_f32 v90, v94, v95
	v_lshlrev_b64 v[94:95], 14, v[98:99]
	v_pk_mul_f32 v[102:103], v[92:93], v[92:93]
	v_lshl_add_u64 v[94:95], s[0:1], 0, v[94:95]
	v_cvt_pk_bf16_f32 v91, v96, v97
	v_cvt_pk_bf16_f32 v92, v100, v101
	v_cvt_pk_bf16_f32 v93, v102, v103
	v_lshl_add_u64 v[94:95], v[94:95], 0, v[128:129]
	v_max_f32_e32 v82, 0, v82
	v_max_f32_e32 v83, 0, v83
	global_store_dwordx4 v[94:95], v[90:93], off
	s_nop 1
	v_pk_mul_f32 v[90:91], v[82:83], v[82:83]
	v_max_f32_e32 v83, v84, v84
	v_max_f32_e32 v82, v88, v88
	v_max_f32_e32 v84, 0, v83
	v_max_f32_e32 v83, v89, v89
	v_max_f32_e32 v86, 0, v86
	v_max_f32_e32 v87, 0, v87
	v_max_f32_e32 v82, 0, v82
	v_max_f32_e32 v83, 0, v83
	v_max_f32_e32 v85, 0, v85
	v_pk_mul_f32 v[86:87], v[86:87], v[86:87]
	v_pk_mul_f32 v[88:89], v[82:83], v[82:83]
	v_pk_mul_f32 v[92:93], v[84:85], v[84:85]
	v_cvt_pk_bf16_f32 v82, v86, v87
	v_cvt_pk_bf16_f32 v83, v88, v89
	v_cvt_pk_bf16_f32 v84, v90, v91
	v_cvt_pk_bf16_f32 v85, v92, v93
	v_max_f32_e32 v74, 0, v74
	v_max_f32_e32 v75, 0, v75
	global_store_dwordx4 v[94:95], v[82:85], off offset:256
	s_nop 1
	v_pk_mul_f32 v[84:85], v[74:75], v[74:75]
	v_max_f32_e32 v75, v76, v76
	v_or_b32_e32 v82, 48, v164
	v_max_f32_e32 v78, 0, v78
	v_max_f32_e32 v79, 0, v79
	v_max_f32_e32 v74, v80, v80
	v_max_f32_e32 v76, 0, v75
	v_max_f32_e32 v75, v81, v81
	v_ashrrev_i32_e32 v83, 31, v82
	v_pk_mul_f32 v[78:79], v[78:79], v[78:79]
	v_max_f32_e32 v74, 0, v74
	v_max_f32_e32 v75, 0, v75
	v_max_f32_e32 v77, 0, v77
	v_pk_mul_f32 v[80:81], v[74:75], v[74:75]
	v_cvt_pk_bf16_f32 v74, v78, v79
	v_lshlrev_b64 v[78:79], 14, v[82:83]
	v_pk_mul_f32 v[86:87], v[76:77], v[76:77]
	v_lshl_add_u64 v[78:79], s[0:1], 0, v[78:79]
	v_cvt_pk_bf16_f32 v75, v80, v81
	v_cvt_pk_bf16_f32 v76, v84, v85
	v_cvt_pk_bf16_f32 v77, v86, v87
	v_lshl_add_u64 v[78:79], v[78:79], 0, v[128:129]
	v_max_f32_e32 v66, 0, v66
	v_max_f32_e32 v67, 0, v67
	global_store_dwordx4 v[78:79], v[74:77], off
	s_nop 1
	v_pk_mul_f32 v[74:75], v[66:67], v[66:67]
	v_max_f32_e32 v67, v68, v68
	v_max_f32_e32 v66, v72, v72
	v_max_f32_e32 v68, 0, v67
	v_max_f32_e32 v67, v73, v73
	v_max_f32_e32 v70, 0, v70
	v_max_f32_e32 v71, 0, v71
	v_max_f32_e32 v66, 0, v66
	v_max_f32_e32 v67, 0, v67
	v_max_f32_e32 v69, 0, v69
	v_pk_mul_f32 v[70:71], v[70:71], v[70:71]
	v_pk_mul_f32 v[72:73], v[66:67], v[66:67]
	v_pk_mul_f32 v[76:77], v[68:69], v[68:69]
	v_cvt_pk_bf16_f32 v66, v70, v71
	v_cvt_pk_bf16_f32 v67, v72, v73
	v_cvt_pk_bf16_f32 v68, v74, v75
	v_cvt_pk_bf16_f32 v69, v76, v77
	v_max_f32_e32 v58, 0, v58
	v_max_f32_e32 v59, 0, v59
	global_store_dwordx4 v[78:79], v[66:69], off offset:256
	s_nop 1
	v_pk_mul_f32 v[66:67], v[58:59], v[58:59]
	v_max_f32_e32 v59, v60, v60
	v_max_f32_e32 v58, v64, v64
	v_max_f32_e32 v60, 0, v59
	v_max_f32_e32 v59, v65, v65
	v_max_f32_e32 v58, 0, v58
	v_max_f32_e32 v59, 0, v59
	v_max_f32_e32 v62, 0, v62
	v_max_f32_e32 v63, 0, v63
	v_max_f32_e32 v61, 0, v61
	v_pk_mul_f32 v[64:65], v[58:59], v[58:59]
	v_pk_mul_f32 v[62:63], v[62:63], v[62:63]
	v_pk_mul_f32 v[68:69], v[60:61], v[60:61]
	v_cvt_pk_bf16_f32 v59, v64, v65
	v_add_co_u32_e32 v64, vcc, s64, v122
	v_cvt_pk_bf16_f32 v58, v62, v63
	v_cvt_pk_bf16_f32 v60, v66, v67
	v_cvt_pk_bf16_f32 v61, v68, v69
	v_addc_co_u32_e32 v65, vcc, 0, v123, vcc
	v_max_f32_e32 v50, 0, v50
	v_max_f32_e32 v51, 0, v51
	global_store_dwordx4 v[64:65], v[58:61], off
	s_nop 1
	v_pk_mul_f32 v[58:59], v[50:51], v[50:51]
	v_max_f32_e32 v51, v52, v52
	v_max_f32_e32 v50, v56, v56
	v_max_f32_e32 v52, 0, v51
	v_max_f32_e32 v51, v57, v57
	v_max_f32_e32 v54, 0, v54
	v_max_f32_e32 v55, 0, v55
	v_max_f32_e32 v50, 0, v50
	v_max_f32_e32 v51, 0, v51
	v_max_f32_e32 v53, 0, v53
	v_pk_mul_f32 v[54:55], v[54:55], v[54:55]
	v_pk_mul_f32 v[56:57], v[50:51], v[50:51]
	v_pk_mul_f32 v[60:61], v[52:53], v[52:53]
	v_lshl_add_u64 v[62:63], v[122:123], 0, s[12:13]
	v_cvt_pk_bf16_f32 v50, v54, v55
	v_cvt_pk_bf16_f32 v51, v56, v57
	v_cvt_pk_bf16_f32 v52, v58, v59
	v_cvt_pk_bf16_f32 v53, v60, v61
	v_max_f32_e32 v42, 0, v42
	v_max_f32_e32 v43, 0, v43
	global_store_dwordx4 v[62:63], v[50:53], off offset:256
	s_nop 1
	v_pk_mul_f32 v[50:51], v[42:43], v[42:43]
	v_max_f32_e32 v43, v44, v44
	v_max_f32_e32 v42, v48, v48
	v_max_f32_e32 v44, 0, v43
	v_max_f32_e32 v43, v49, v49
	v_max_f32_e32 v42, 0, v42
	v_max_f32_e32 v43, 0, v43
	v_max_f32_e32 v46, 0, v46
	v_max_f32_e32 v47, 0, v47
	v_max_f32_e32 v45, 0, v45
	v_pk_mul_f32 v[48:49], v[42:43], v[42:43]
	v_pk_mul_f32 v[46:47], v[46:47], v[46:47]
	v_pk_mul_f32 v[52:53], v[44:45], v[44:45]
	v_cvt_pk_bf16_f32 v43, v48, v49
	v_add_co_u32_e32 v48, vcc, s65, v122
	v_cvt_pk_bf16_f32 v42, v46, v47
	v_cvt_pk_bf16_f32 v44, v50, v51
	v_cvt_pk_bf16_f32 v45, v52, v53
	v_addc_co_u32_e32 v49, vcc, 0, v123, vcc
	v_max_f32_e32 v34, 0, v34
	v_max_f32_e32 v35, 0, v35
	global_store_dwordx4 v[48:49], v[42:45], off
	s_nop 1
	v_pk_mul_f32 v[42:43], v[34:35], v[34:35]
	v_max_f32_e32 v35, v36, v36
	v_max_f32_e32 v34, v40, v40
	v_max_f32_e32 v36, 0, v35
	v_max_f32_e32 v35, v41, v41
	v_max_f32_e32 v38, 0, v38
	v_max_f32_e32 v39, 0, v39
	v_max_f32_e32 v34, 0, v34
	v_max_f32_e32 v35, 0, v35
	v_max_f32_e32 v37, 0, v37
	v_pk_mul_f32 v[38:39], v[38:39], v[38:39]
	v_pk_mul_f32 v[40:41], v[34:35], v[34:35]
	v_pk_mul_f32 v[44:45], v[36:37], v[36:37]
	v_lshl_add_u64 v[46:47], v[122:123], 0, s[14:15]
	v_cvt_pk_bf16_f32 v34, v38, v39
	v_cvt_pk_bf16_f32 v35, v40, v41
	v_cvt_pk_bf16_f32 v36, v42, v43
	v_cvt_pk_bf16_f32 v37, v44, v45
	v_max_f32_e32 v26, 0, v26
	v_max_f32_e32 v27, 0, v27
	global_store_dwordx4 v[46:47], v[34:37], off offset:256
	s_nop 1
	v_pk_mul_f32 v[34:35], v[26:27], v[26:27]
	v_max_f32_e32 v27, v28, v28
	v_max_f32_e32 v26, v32, v32
	v_max_f32_e32 v28, 0, v27
	v_max_f32_e32 v27, v33, v33
	v_max_f32_e32 v26, 0, v26
	v_max_f32_e32 v27, 0, v27
	v_max_f32_e32 v30, 0, v30
	v_max_f32_e32 v31, 0, v31
	v_max_f32_e32 v29, 0, v29
	v_pk_mul_f32 v[32:33], v[26:27], v[26:27]
	v_pk_mul_f32 v[30:31], v[30:31], v[30:31]
	v_pk_mul_f32 v[36:37], v[28:29], v[28:29]
	v_cvt_pk_bf16_f32 v27, v32, v33
	v_add_co_u32_e32 v32, vcc, s66, v122
	v_cvt_pk_bf16_f32 v26, v30, v31
	v_cvt_pk_bf16_f32 v28, v34, v35
	v_cvt_pk_bf16_f32 v29, v36, v37
	v_addc_co_u32_e32 v33, vcc, 0, v123, vcc
	v_max_f32_e32 v18, 0, v18
	v_max_f32_e32 v19, 0, v19
	global_store_dwordx4 v[32:33], v[26:29], off
	s_nop 1
	v_pk_mul_f32 v[26:27], v[18:19], v[18:19]
	v_max_f32_e32 v19, v20, v20
	v_max_f32_e32 v18, v24, v24
	v_max_f32_e32 v20, 0, v19
	v_max_f32_e32 v19, v25, v25
	v_max_f32_e32 v22, 0, v22
	v_max_f32_e32 v23, 0, v23
	v_max_f32_e32 v18, 0, v18
	v_max_f32_e32 v19, 0, v19
	v_max_f32_e32 v21, 0, v21
	v_pk_mul_f32 v[22:23], v[22:23], v[22:23]
	v_pk_mul_f32 v[24:25], v[18:19], v[18:19]
	v_pk_mul_f32 v[28:29], v[20:21], v[20:21]
	v_lshl_add_u64 v[30:31], v[122:123], 0, s[16:17]
	v_cvt_pk_bf16_f32 v18, v22, v23
	v_cvt_pk_bf16_f32 v19, v24, v25
	v_cvt_pk_bf16_f32 v20, v26, v27
	v_cvt_pk_bf16_f32 v21, v28, v29
	v_max_f32_e32 v10, 0, v10
	v_max_f32_e32 v11, 0, v11
	global_store_dwordx4 v[30:31], v[18:21], off offset:256
	s_nop 1
	v_pk_mul_f32 v[18:19], v[10:11], v[10:11]
	v_max_f32_e32 v11, v12, v12
	v_max_f32_e32 v10, v16, v16
	v_max_f32_e32 v12, 0, v11
	v_max_f32_e32 v11, v17, v17
	v_max_f32_e32 v10, 0, v10
	v_max_f32_e32 v11, 0, v11
	v_max_f32_e32 v14, 0, v14
	v_max_f32_e32 v15, 0, v15
	v_max_f32_e32 v13, 0, v13
	v_pk_mul_f32 v[16:17], v[10:11], v[10:11]
	v_pk_mul_f32 v[14:15], v[14:15], v[14:15]
	v_pk_mul_f32 v[20:21], v[12:13], v[12:13]
	v_cvt_pk_bf16_f32 v11, v16, v17
	v_add_co_u32_e32 v16, vcc, s67, v122
	v_cvt_pk_bf16_f32 v10, v14, v15
	v_cvt_pk_bf16_f32 v12, v18, v19
	v_cvt_pk_bf16_f32 v13, v20, v21
	v_addc_co_u32_e32 v17, vcc, 0, v123, vcc
	v_max_f32_e32 v2, 0, v2
	v_max_f32_e32 v3, 0, v3
	global_store_dwordx4 v[16:17], v[10:13], off
	s_nop 1
	v_pk_mul_f32 v[10:11], v[2:3], v[2:3]
	v_max_f32_e32 v3, v4, v4
	v_max_f32_e32 v2, v8, v8
	v_max_f32_e32 v4, 0, v3
	v_max_f32_e32 v3, v9, v9
	v_max_f32_e32 v6, 0, v6
	v_max_f32_e32 v7, 0, v7
	v_max_f32_e32 v2, 0, v2
	v_max_f32_e32 v3, 0, v3
	v_max_f32_e32 v5, 0, v5
	v_pk_mul_f32 v[6:7], v[6:7], v[6:7]
	v_pk_mul_f32 v[8:9], v[2:3], v[2:3]
	v_pk_mul_f32 v[12:13], v[4:5], v[4:5]
	v_lshl_add_u64 v[14:15], v[122:123], 0, s[18:19]
	v_cvt_pk_bf16_f32 v2, v6, v7
	v_cvt_pk_bf16_f32 v3, v8, v9
	v_cvt_pk_bf16_f32 v4, v10, v11
	v_cvt_pk_bf16_f32 v5, v12, v13
	s_andn2_b64 vcc, exec, s[4:5]
	s_mov_b64 s[4:5], -1
	global_store_dwordx4 v[14:15], v[2:5], off offset:256
	s_cbranch_vccnz .LBB0_699
	s_andn2_b64 vcc, exec, s[6:7]
	s_cbranch_vccnz .LBB0_698
	s_barrier
	s_branch .LBB0_698

.LBB0_860:
	v_lshl_add_u32 v168, s16, 8, v161
	v_max_f32_e32 v126, 0, v126
	v_max_f32_e32 v122, 0, v122
	v_max_f32_e32 v127, 0, v127
	v_max_f32_e32 v123, 0, v123
	v_lshl_or_b32 v170, s17, 8, v163
	v_ashrrev_i32_e32 v169, 31, v168
	v_pk_mul_f32 v[126:127], v[126:127], v[126:127]
	v_pk_mul_f32 v[122:123], v[122:123], v[122:123]
	v_max_f32_e32 v128, 0, v128
	v_max_f32_e32 v124, 0, v124
	v_max_f32_e32 v129, 0, v129
	v_max_f32_e32 v125, 0, v125
	v_ashrrev_i32_e32 v171, 31, v170
	v_pk_mul_f32 v[128:129], v[128:129], v[128:129]
	v_pk_mul_f32 v[172:173], v[124:125], v[124:125]
	v_cvt_pk_bf16_f32 v124, v126, v127
	v_cvt_pk_bf16_f32 v126, v122, v123
	v_lshlrev_b64 v[122:123], 14, v[168:169]
	v_cvt_pk_bf16_f32 v125, v128, v129
	v_lshl_add_u64 v[122:123], s[0:1], 0, v[122:123]
	v_lshlrev_b64 v[128:129], 1, v[170:171]
	v_cvt_pk_bf16_f32 v127, v172, v173
	v_lshl_add_u64 v[122:123], v[122:123], 0, v[128:129]
	v_max_f32_e32 v114, 0, v114
	v_max_f32_e32 v115, 0, v115
	global_store_dwordx4 v[122:123], v[124:127], off
	s_nop 1
	v_pk_mul_f32 v[124:125], v[114:115], v[114:115]
	v_max_f32_e32 v115, v116, v116
	v_max_f32_e32 v114, v120, v120
	v_max_f32_e32 v116, 0, v115
	v_max_f32_e32 v115, v121, v121
	v_max_f32_e32 v118, 0, v118
	v_max_f32_e32 v119, 0, v119
	v_max_f32_e32 v114, 0, v114
	v_max_f32_e32 v115, 0, v115
	v_max_f32_e32 v117, 0, v117
	v_pk_mul_f32 v[118:119], v[118:119], v[118:119]
	v_pk_mul_f32 v[120:121], v[114:115], v[114:115]
	v_pk_mul_f32 v[126:127], v[116:117], v[116:117]
	v_cvt_pk_bf16_f32 v114, v118, v119
	v_cvt_pk_bf16_f32 v115, v120, v121
	v_cvt_pk_bf16_f32 v116, v124, v125
	v_cvt_pk_bf16_f32 v117, v126, v127
	v_max_f32_e32 v106, 0, v106
	v_max_f32_e32 v107, 0, v107
	global_store_dwordx4 v[122:123], v[114:117], off offset:256
	s_nop 1
	v_pk_mul_f32 v[116:117], v[106:107], v[106:107]
	v_max_f32_e32 v107, v108, v108
	v_or_b32_e32 v114, 16, v168
	v_max_f32_e32 v110, 0, v110
	v_max_f32_e32 v111, 0, v111
	v_max_f32_e32 v106, v112, v112
	v_max_f32_e32 v108, 0, v107
	v_max_f32_e32 v107, v113, v113
	v_ashrrev_i32_e32 v115, 31, v114
	v_pk_mul_f32 v[110:111], v[110:111], v[110:111]
	v_max_f32_e32 v106, 0, v106
	v_max_f32_e32 v107, 0, v107
	v_max_f32_e32 v109, 0, v109
	v_pk_mul_f32 v[112:113], v[106:107], v[106:107]
	v_cvt_pk_bf16_f32 v106, v110, v111
	v_lshlrev_b64 v[110:111], 14, v[114:115]
	v_pk_mul_f32 v[118:119], v[108:109], v[108:109]
	v_lshl_add_u64 v[110:111], s[0:1], 0, v[110:111]
	v_cvt_pk_bf16_f32 v107, v112, v113
	v_cvt_pk_bf16_f32 v108, v116, v117
	v_cvt_pk_bf16_f32 v109, v118, v119
	v_lshl_add_u64 v[110:111], v[110:111], 0, v[128:129]
	v_max_f32_e32 v98, 0, v98
	v_max_f32_e32 v99, 0, v99
	global_store_dwordx4 v[110:111], v[106:109], off
	s_nop 1
	v_pk_mul_f32 v[106:107], v[98:99], v[98:99]
	v_max_f32_e32 v99, v100, v100
	v_max_f32_e32 v98, v104, v104
	v_max_f32_e32 v100, 0, v99
	v_max_f32_e32 v99, v105, v105
	v_max_f32_e32 v102, 0, v102
	v_max_f32_e32 v103, 0, v103
	v_max_f32_e32 v98, 0, v98
	v_max_f32_e32 v99, 0, v99
	v_max_f32_e32 v101, 0, v101
	v_pk_mul_f32 v[102:103], v[102:103], v[102:103]
	v_pk_mul_f32 v[104:105], v[98:99], v[98:99]
	v_pk_mul_f32 v[108:109], v[100:101], v[100:101]
	v_cvt_pk_bf16_f32 v98, v102, v103
	v_cvt_pk_bf16_f32 v99, v104, v105
	v_cvt_pk_bf16_f32 v100, v106, v107
	v_cvt_pk_bf16_f32 v101, v108, v109
	v_max_f32_e32 v90, 0, v90
	v_max_f32_e32 v91, 0, v91
	global_store_dwordx4 v[110:111], v[98:101], off offset:256
	s_nop 1
	v_pk_mul_f32 v[100:101], v[90:91], v[90:91]
	v_max_f32_e32 v91, v92, v92
	v_or_b32_e32 v98, 32, v168
	v_max_f32_e32 v94, 0, v94
	v_max_f32_e32 v95, 0, v95
	v_max_f32_e32 v90, v96, v96
	v_max_f32_e32 v92, 0, v91
	v_max_f32_e32 v91, v97, v97
	v_ashrrev_i32_e32 v99, 31, v98
	v_pk_mul_f32 v[94:95], v[94:95], v[94:95]
	v_max_f32_e32 v90, 0, v90
	v_max_f32_e32 v91, 0, v91
	v_max_f32_e32 v93, 0, v93
	v_pk_mul_f32 v[96:97], v[90:91], v[90:91]
	v_cvt_pk_bf16_f32 v90, v94, v95
	v_lshlrev_b64 v[94:95], 14, v[98:99]
	v_pk_mul_f32 v[102:103], v[92:93], v[92:93]
	v_lshl_add_u64 v[94:95], s[0:1], 0, v[94:95]
	v_cvt_pk_bf16_f32 v91, v96, v97
	v_cvt_pk_bf16_f32 v92, v100, v101
	v_cvt_pk_bf16_f32 v93, v102, v103
	v_lshl_add_u64 v[94:95], v[94:95], 0, v[128:129]
	v_max_f32_e32 v82, 0, v82
	v_max_f32_e32 v83, 0, v83
	global_store_dwordx4 v[94:95], v[90:93], off
	s_nop 1
	v_pk_mul_f32 v[90:91], v[82:83], v[82:83]
	v_max_f32_e32 v83, v84, v84
	v_max_f32_e32 v82, v88, v88
	v_max_f32_e32 v84, 0, v83
	v_max_f32_e32 v83, v89, v89
	v_max_f32_e32 v86, 0, v86
	v_max_f32_e32 v87, 0, v87
	v_max_f32_e32 v82, 0, v82
	v_max_f32_e32 v83, 0, v83
	v_max_f32_e32 v85, 0, v85
	v_pk_mul_f32 v[86:87], v[86:87], v[86:87]
	v_pk_mul_f32 v[88:89], v[82:83], v[82:83]
	v_pk_mul_f32 v[92:93], v[84:85], v[84:85]
	v_cvt_pk_bf16_f32 v82, v86, v87
	v_cvt_pk_bf16_f32 v83, v88, v89
	v_cvt_pk_bf16_f32 v84, v90, v91
	v_cvt_pk_bf16_f32 v85, v92, v93
	v_max_f32_e32 v74, 0, v74
	v_max_f32_e32 v75, 0, v75
	global_store_dwordx4 v[94:95], v[82:85], off offset:256
	s_nop 1
	v_pk_mul_f32 v[84:85], v[74:75], v[74:75]
	v_max_f32_e32 v75, v76, v76
	v_or_b32_e32 v82, 48, v168
	v_max_f32_e32 v78, 0, v78
	v_max_f32_e32 v79, 0, v79
	v_max_f32_e32 v74, v80, v80
	v_max_f32_e32 v76, 0, v75
	v_max_f32_e32 v75, v81, v81
	v_ashrrev_i32_e32 v83, 31, v82
	v_pk_mul_f32 v[78:79], v[78:79], v[78:79]
	v_max_f32_e32 v74, 0, v74
	v_max_f32_e32 v75, 0, v75
	v_max_f32_e32 v77, 0, v77
	v_pk_mul_f32 v[80:81], v[74:75], v[74:75]
	v_cvt_pk_bf16_f32 v74, v78, v79
	v_lshlrev_b64 v[78:79], 14, v[82:83]
	v_pk_mul_f32 v[86:87], v[76:77], v[76:77]
	v_lshl_add_u64 v[78:79], s[0:1], 0, v[78:79]
	v_cvt_pk_bf16_f32 v75, v80, v81
	v_cvt_pk_bf16_f32 v76, v84, v85
	v_cvt_pk_bf16_f32 v77, v86, v87
	v_lshl_add_u64 v[78:79], v[78:79], 0, v[128:129]
	v_max_f32_e32 v66, 0, v66
	v_max_f32_e32 v67, 0, v67
	global_store_dwordx4 v[78:79], v[74:77], off
	s_nop 1
	v_pk_mul_f32 v[74:75], v[66:67], v[66:67]
	v_max_f32_e32 v67, v68, v68
	v_max_f32_e32 v66, v72, v72
	v_max_f32_e32 v68, 0, v67
	v_max_f32_e32 v67, v73, v73
	v_max_f32_e32 v70, 0, v70
	v_max_f32_e32 v71, 0, v71
	v_max_f32_e32 v66, 0, v66
	v_max_f32_e32 v67, 0, v67
	v_max_f32_e32 v69, 0, v69
	v_pk_mul_f32 v[70:71], v[70:71], v[70:71]
	v_pk_mul_f32 v[72:73], v[66:67], v[66:67]
	v_pk_mul_f32 v[76:77], v[68:69], v[68:69]
	v_cvt_pk_bf16_f32 v66, v70, v71
	v_cvt_pk_bf16_f32 v67, v72, v73
	v_cvt_pk_bf16_f32 v68, v74, v75
	v_cvt_pk_bf16_f32 v69, v76, v77
	v_max_f32_e32 v58, 0, v58
	v_max_f32_e32 v59, 0, v59
	global_store_dwordx4 v[78:79], v[66:69], off offset:256
	s_nop 1
	v_pk_mul_f32 v[66:67], v[58:59], v[58:59]
	v_max_f32_e32 v59, v60, v60
	v_max_f32_e32 v62, 0, v62
	v_max_f32_e32 v63, 0, v63
	v_max_f32_e32 v58, v64, v64
	v_max_f32_e32 v60, 0, v59
	v_max_f32_e32 v59, v65, v65
	v_pk_mul_f32 v[62:63], v[62:63], v[62:63]
	v_max_f32_e32 v58, 0, v58
	v_max_f32_e32 v59, 0, v59
	s_mov_b64 s[16:17], 0x200000
	v_max_f32_e32 v61, 0, v61
	v_pk_mul_f32 v[64:65], v[58:59], v[58:59]
	v_cvt_pk_bf16_f32 v58, v62, v63
	v_lshl_add_u64 v[62:63], v[122:123], 0, s[16:17]
	s_mov_b32 s16, 0x200000
	v_pk_mul_f32 v[68:69], v[60:61], v[60:61]
	v_cvt_pk_bf16_f32 v59, v64, v65
	v_add_co_u32_e32 v64, vcc, s16, v122
	v_cvt_pk_bf16_f32 v60, v66, v67
	v_cvt_pk_bf16_f32 v61, v68, v69
	v_addc_co_u32_e32 v65, vcc, 0, v123, vcc
	v_max_f32_e32 v50, 0, v50
	v_max_f32_e32 v51, 0, v51
	global_store_dwordx4 v[64:65], v[58:61], off
	s_nop 1
	v_pk_mul_f32 v[58:59], v[50:51], v[50:51]
	v_max_f32_e32 v51, v52, v52
	v_max_f32_e32 v50, v56, v56
	v_max_f32_e32 v52, 0, v51
	v_max_f32_e32 v51, v57, v57
	v_max_f32_e32 v54, 0, v54
	v_max_f32_e32 v55, 0, v55
	v_max_f32_e32 v50, 0, v50
	v_max_f32_e32 v51, 0, v51
	v_max_f32_e32 v53, 0, v53
	v_pk_mul_f32 v[54:55], v[54:55], v[54:55]
	v_pk_mul_f32 v[56:57], v[50:51], v[50:51]
	v_pk_mul_f32 v[60:61], v[52:53], v[52:53]
	v_cvt_pk_bf16_f32 v50, v54, v55
	v_cvt_pk_bf16_f32 v51, v56, v57
	v_cvt_pk_bf16_f32 v52, v58, v59
	v_cvt_pk_bf16_f32 v53, v60, v61
	v_max_f32_e32 v42, 0, v42
	v_max_f32_e32 v43, 0, v43
	global_store_dwordx4 v[62:63], v[50:53], off offset:256
	s_nop 1
	v_pk_mul_f32 v[50:51], v[42:43], v[42:43]
	v_max_f32_e32 v43, v44, v44
	v_max_f32_e32 v46, 0, v46
	v_max_f32_e32 v47, 0, v47
	v_max_f32_e32 v42, v48, v48
	v_max_f32_e32 v44, 0, v43
	v_max_f32_e32 v43, v49, v49
	v_pk_mul_f32 v[46:47], v[46:47], v[46:47]
	v_max_f32_e32 v42, 0, v42
	v_max_f32_e32 v43, 0, v43
	s_mov_b64 s[16:17], 0x240000
	v_max_f32_e32 v45, 0, v45
	v_pk_mul_f32 v[48:49], v[42:43], v[42:43]
	v_cvt_pk_bf16_f32 v42, v46, v47
	v_lshl_add_u64 v[46:47], v[122:123], 0, s[16:17]
	s_mov_b32 s16, 0x240000
	v_pk_mul_f32 v[52:53], v[44:45], v[44:45]
	v_cvt_pk_bf16_f32 v43, v48, v49
	v_add_co_u32_e32 v48, vcc, s16, v122
	v_cvt_pk_bf16_f32 v44, v50, v51
	v_cvt_pk_bf16_f32 v45, v52, v53
	v_addc_co_u32_e32 v49, vcc, 0, v123, vcc
	v_max_f32_e32 v34, 0, v34
	v_max_f32_e32 v35, 0, v35
	global_store_dwordx4 v[48:49], v[42:45], off
	s_nop 1
	v_pk_mul_f32 v[42:43], v[34:35], v[34:35]
	v_max_f32_e32 v35, v36, v36
	v_max_f32_e32 v34, v40, v40
	v_max_f32_e32 v36, 0, v35
	v_max_f32_e32 v35, v41, v41
	v_max_f32_e32 v38, 0, v38
	v_max_f32_e32 v39, 0, v39
	v_max_f32_e32 v34, 0, v34
	v_max_f32_e32 v35, 0, v35
	v_max_f32_e32 v37, 0, v37
	v_pk_mul_f32 v[38:39], v[38:39], v[38:39]
	v_pk_mul_f32 v[40:41], v[34:35], v[34:35]
	v_pk_mul_f32 v[44:45], v[36:37], v[36:37]
	v_cvt_pk_bf16_f32 v34, v38, v39
	v_cvt_pk_bf16_f32 v35, v40, v41
	v_cvt_pk_bf16_f32 v36, v42, v43
	v_cvt_pk_bf16_f32 v37, v44, v45
	v_max_f32_e32 v26, 0, v26
	v_max_f32_e32 v27, 0, v27
	global_store_dwordx4 v[46:47], v[34:37], off offset:256
	s_nop 1
	v_pk_mul_f32 v[34:35], v[26:27], v[26:27]
	v_max_f32_e32 v27, v28, v28
	v_max_f32_e32 v30, 0, v30
	v_max_f32_e32 v31, 0, v31
	v_max_f32_e32 v26, v32, v32
	v_max_f32_e32 v28, 0, v27
	v_max_f32_e32 v27, v33, v33
	v_pk_mul_f32 v[30:31], v[30:31], v[30:31]
	v_max_f32_e32 v26, 0, v26
	v_max_f32_e32 v27, 0, v27
	s_mov_b64 s[16:17], 0x280000
	v_max_f32_e32 v29, 0, v29
	v_pk_mul_f32 v[32:33], v[26:27], v[26:27]
	v_cvt_pk_bf16_f32 v26, v30, v31
	v_lshl_add_u64 v[30:31], v[122:123], 0, s[16:17]
	s_mov_b32 s16, 0x280000
	v_pk_mul_f32 v[36:37], v[28:29], v[28:29]
	v_cvt_pk_bf16_f32 v27, v32, v33
	v_add_co_u32_e32 v32, vcc, s16, v122
	v_cvt_pk_bf16_f32 v28, v34, v35
	v_cvt_pk_bf16_f32 v29, v36, v37
	v_addc_co_u32_e32 v33, vcc, 0, v123, vcc
	v_max_f32_e32 v18, 0, v18
	v_max_f32_e32 v19, 0, v19
	global_store_dwordx4 v[32:33], v[26:29], off
	s_nop 1
	v_pk_mul_f32 v[26:27], v[18:19], v[18:19]
	v_max_f32_e32 v19, v20, v20
	v_max_f32_e32 v18, v24, v24
	v_max_f32_e32 v20, 0, v19
	v_max_f32_e32 v19, v25, v25
	v_max_f32_e32 v22, 0, v22
	v_max_f32_e32 v23, 0, v23
	v_max_f32_e32 v18, 0, v18
	v_max_f32_e32 v19, 0, v19
	v_max_f32_e32 v21, 0, v21
	v_pk_mul_f32 v[22:23], v[22:23], v[22:23]
	v_pk_mul_f32 v[24:25], v[18:19], v[18:19]
	v_pk_mul_f32 v[28:29], v[20:21], v[20:21]
	v_cvt_pk_bf16_f32 v18, v22, v23
	v_cvt_pk_bf16_f32 v19, v24, v25
	v_cvt_pk_bf16_f32 v20, v26, v27
	v_cvt_pk_bf16_f32 v21, v28, v29
	v_max_f32_e32 v10, 0, v10
	v_max_f32_e32 v11, 0, v11
	global_store_dwordx4 v[30:31], v[18:21], off offset:256
	s_nop 1
	v_pk_mul_f32 v[18:19], v[10:11], v[10:11]
	v_max_f32_e32 v11, v12, v12
	v_max_f32_e32 v14, 0, v14
	v_max_f32_e32 v15, 0, v15
	v_max_f32_e32 v10, v16, v16
	v_max_f32_e32 v12, 0, v11
	v_max_f32_e32 v11, v17, v17
	v_pk_mul_f32 v[14:15], v[14:15], v[14:15]
	v_max_f32_e32 v10, 0, v10
	v_max_f32_e32 v11, 0, v11
	s_mov_b64 s[16:17], 0x2c0000
	v_max_f32_e32 v13, 0, v13
	v_pk_mul_f32 v[16:17], v[10:11], v[10:11]
	v_cvt_pk_bf16_f32 v10, v14, v15
	v_lshl_add_u64 v[14:15], v[122:123], 0, s[16:17]
	s_mov_b32 s16, 0x2c0000
	v_pk_mul_f32 v[20:21], v[12:13], v[12:13]
	v_cvt_pk_bf16_f32 v11, v16, v17
	v_add_co_u32_e32 v16, vcc, s16, v122
	v_cvt_pk_bf16_f32 v12, v18, v19
	v_cvt_pk_bf16_f32 v13, v20, v21
	v_addc_co_u32_e32 v17, vcc, 0, v123, vcc
	v_max_f32_e32 v2, 0, v2
	v_max_f32_e32 v3, 0, v3
	global_store_dwordx4 v[16:17], v[10:13], off
	s_nop 1
	v_pk_mul_f32 v[10:11], v[2:3], v[2:3]
	v_max_f32_e32 v3, v4, v4
	v_max_f32_e32 v2, v8, v8
	v_max_f32_e32 v4, 0, v3
	v_max_f32_e32 v3, v9, v9
	v_max_f32_e32 v6, 0, v6
	v_max_f32_e32 v7, 0, v7
	v_max_f32_e32 v2, 0, v2
	v_max_f32_e32 v3, 0, v3
	v_max_f32_e32 v5, 0, v5
	v_pk_mul_f32 v[6:7], v[6:7], v[6:7]
	v_pk_mul_f32 v[8:9], v[2:3], v[2:3]
	v_pk_mul_f32 v[12:13], v[4:5], v[4:5]
	v_cvt_pk_bf16_f32 v2, v6, v7
	v_cvt_pk_bf16_f32 v3, v8, v9
	v_cvt_pk_bf16_f32 v4, v10, v11
	v_cvt_pk_bf16_f32 v5, v12, v13
	s_mov_b64 s[16:17], -1
	s_and_b64 vcc, exec, s[38:39]
	global_store_dwordx4 v[14:15], v[2:5], off offset:256
	s_cbranch_vccz .LBB0_849
	s_andn2_b64 vcc, exec, s[6:7]
	s_cbranch_vccnz .LBB0_848
	s_barrier
	s_branch .LBB0_848
